# GEMM loops: snake order over the accumulator grid with alternating K order: every MFMA shares its accumulator (pair) or one fragment operand (pair boundary) with its predecessor
# baseline (speedup 1.0000x reference)
.LBB0_178:
	s_add_u32 s26, s22, 0xfffc0080
	s_addc_u32 s27, s23, -1
	s_add_i32 s34, 0, 0x10000
	s_cmp_eq_u32 s59, 12
	s_cselect_b32 s31, s9, s27
	s_cselect_b32 s30, s15, s26
	s_cselect_b32 s27, s13, s58
	s_cselect_b32 s26, s56, s57
	s_add_i32 s35, 0, 0x14000
	v_add_u32_e32 v140, s34, v195
	v_add_u32_e32 v166, s35, v195
	ds_read_b128 v[128:131], v140
	ds_read_b128 v[132:135], v140 offset:1024
	ds_read_b128 v[136:139], v140 offset:2048
	ds_read_b128 v[140:143], v140 offset:3072
	ds_read_b128 v[144:147], v166
	ds_read_b128 v[148:151], v166 offset:1024
	ds_read_b128 v[180:183], v166 offset:2048
	ds_read_b128 v[184:187], v166 offset:3072
	s_add_i32 m0, s49, 0xc000
	ds_read_b128 v[188:191], v200
	ds_read_b128 v[202:205], v200 offset:1024
	ds_read_b128 v[206:209], v200 offset:2048
	ds_read_b128 v[210:213], v200 offset:3072
	ds_read_b128 v[228:231], v200 offset:4096
	ds_read_b128 v[232:235], v200 offset:5120
	ds_read_b128 v[236:239], v200 offset:6144
	ds_read_b128 v[240:243], v200 offset:7168
	global_load_lds_dwordx4 v160, s[22:23]
	s_add_i32 m0, s49, 0xe000
	s_nop 0
	global_load_lds_dwordx4 v162, s[22:23]
	s_waitcnt vmcnt(8)
	s_waitcnt lgkmcnt(0)
	s_barrier
	s_setprio 1
	s_waitcnt lgkmcnt(0)
	v_mfma_f32_16x16x32_bf16 v[124:127], v[128:131], v[188:191], v[124:127]
	v_mfma_f32_16x16x32_bf16 v[124:127], v[132:135], v[202:205], v[124:127]
	v_mfma_f32_16x16x32_bf16 v[112:115], v[132:135], v[210:213], v[112:115]
	v_mfma_f32_16x16x32_bf16 v[112:115], v[128:131], v[206:209], v[112:115]
	v_mfma_f32_16x16x32_bf16 v[96:99], v[128:131], v[228:231], v[96:99]
	v_mfma_f32_16x16x32_bf16 v[96:99], v[132:135], v[232:235], v[96:99]
	v_mfma_f32_16x16x32_bf16 v[80:83], v[132:135], v[240:243], v[80:83]
	v_mfma_f32_16x16x32_bf16 v[80:83], v[128:131], v[236:239], v[80:83]
	v_mfma_f32_16x16x32_bf16 v[72:75], v[136:139], v[236:239], v[72:75]
	v_mfma_f32_16x16x32_bf16 v[72:75], v[140:143], v[240:243], v[72:75]
	v_mfma_f32_16x16x32_bf16 v[88:91], v[140:143], v[232:235], v[88:91]
	v_mfma_f32_16x16x32_bf16 v[88:91], v[136:139], v[228:231], v[88:91]
	v_mfma_f32_16x16x32_bf16 v[104:107], v[136:139], v[206:209], v[104:107]
	v_mfma_f32_16x16x32_bf16 v[104:107], v[140:143], v[210:213], v[104:107]
	v_mfma_f32_16x16x32_bf16 v[120:123], v[140:143], v[202:205], v[120:123]
	v_mfma_f32_16x16x32_bf16 v[120:123], v[136:139], v[188:191], v[120:123]
	s_setprio 0
	s_setprio 1
	v_mfma_f32_16x16x32_bf16 v[116:119], v[144:147], v[188:191], v[116:119]
	v_mfma_f32_16x16x32_bf16 v[116:119], v[148:151], v[202:205], v[116:119]
	v_mfma_f32_16x16x32_bf16 v[100:103], v[148:151], v[210:213], v[100:103]
	v_mfma_f32_16x16x32_bf16 v[100:103], v[144:147], v[206:209], v[100:103]
	v_mfma_f32_16x16x32_bf16 v[84:87], v[144:147], v[228:231], v[84:87]
	v_mfma_f32_16x16x32_bf16 v[84:87], v[148:151], v[232:235], v[84:87]
	v_mfma_f32_16x16x32_bf16 v[68:71], v[148:151], v[240:243], v[68:71]
	v_mfma_f32_16x16x32_bf16 v[68:71], v[144:147], v[236:239], v[68:71]
	v_mfma_f32_16x16x32_bf16 v[64:67], v[180:183], v[236:239], v[64:67]
	v_mfma_f32_16x16x32_bf16 v[64:67], v[184:187], v[240:243], v[64:67]
	v_mfma_f32_16x16x32_bf16 v[76:79], v[184:187], v[232:235], v[76:79]
	v_mfma_f32_16x16x32_bf16 v[76:79], v[180:183], v[228:231], v[76:79]
	v_mfma_f32_16x16x32_bf16 v[92:95], v[180:183], v[206:209], v[92:95]
	v_mfma_f32_16x16x32_bf16 v[92:95], v[184:187], v[210:213], v[92:95]
	v_mfma_f32_16x16x32_bf16 v[108:111], v[184:187], v[202:205], v[108:111]
	v_mfma_f32_16x16x32_bf16 v[108:111], v[180:183], v[188:191], v[108:111]
	s_setprio 0
	s_barrier
	s_add_i32 s34, s34, s45
	s_add_u32 s98, s26, s20
	s_addc_u32 s99, s27, s21
	s_mov_b32 m0, s34
	ds_read_b128 v[188:191], v200 offset:16384
	ds_read_b128 v[202:205], v200 offset:17408
	ds_read_b128 v[206:209], v200 offset:18432
	ds_read_b128 v[210:213], v200 offset:19456
	ds_read_b128 v[228:231], v200 offset:20480
	ds_read_b128 v[232:235], v200 offset:21504
	ds_read_b128 v[236:239], v200 offset:22528
	ds_read_b128 v[240:243], v200 offset:23552
	global_load_lds_dwordx4 v168, s[26:27]
	s_add_i32 m0, s34, 0x2000
	s_add_u32 s36, s26, 0x40000
	s_addc_u32 s37, s27, 0
	s_add_i32 s34, s35, s45
	global_load_lds_dwordx4 v152, s[26:27]
	s_mov_b32 m0, s34
	s_nop 0
	global_load_lds_dwordx4 v168, s[36:37]
	s_add_i32 m0, s34, 0x2000
	s_nop 0
	global_load_lds_dwordx4 v152, s[36:37]
	s_add_u32 s100, s30, s20
	s_addc_u32 s101, s31, s21
	s_mov_b32 m0, s49
	s_nop 0
	global_load_lds_dwordx4 v156, s[30:31]
	s_mov_b32 m0, s50
	s_nop 0
	global_load_lds_dwordx4 v154, s[30:31]
	s_waitcnt vmcnt(8)
	s_waitcnt lgkmcnt(0)
	s_barrier
	s_setprio 1
	s_waitcnt lgkmcnt(0)
	v_mfma_f32_16x16x32_bf16 v[60:63], v[128:131], v[188:191], v[60:63]
	v_mfma_f32_16x16x32_bf16 v[60:63], v[132:135], v[202:205], v[60:63]
	v_mfma_f32_16x16x32_bf16 v[48:51], v[132:135], v[210:213], v[48:51]
	v_mfma_f32_16x16x32_bf16 v[48:51], v[128:131], v[206:209], v[48:51]
	v_mfma_f32_16x16x32_bf16 v[32:35], v[128:131], v[228:231], v[32:35]
	v_mfma_f32_16x16x32_bf16 v[32:35], v[132:135], v[232:235], v[32:35]
	v_mfma_f32_16x16x32_bf16 v[16:19], v[132:135], v[240:243], v[16:19]
	v_mfma_f32_16x16x32_bf16 v[16:19], v[128:131], v[236:239], v[16:19]
	v_mfma_f32_16x16x32_bf16 v[8:11], v[136:139], v[236:239], v[8:11]
	v_mfma_f32_16x16x32_bf16 v[8:11], v[140:143], v[240:243], v[8:11]
	v_mfma_f32_16x16x32_bf16 v[24:27], v[140:143], v[232:235], v[24:27]
	v_mfma_f32_16x16x32_bf16 v[24:27], v[136:139], v[228:231], v[24:27]
	v_mfma_f32_16x16x32_bf16 v[40:43], v[136:139], v[206:209], v[40:43]
	v_mfma_f32_16x16x32_bf16 v[40:43], v[140:143], v[210:213], v[40:43]
	v_mfma_f32_16x16x32_bf16 v[56:59], v[140:143], v[202:205], v[56:59]
	v_mfma_f32_16x16x32_bf16 v[56:59], v[136:139], v[188:191], v[56:59]
	s_setprio 0
	s_setprio 1
	v_mfma_f32_16x16x32_bf16 v[52:55], v[144:147], v[188:191], v[52:55]
	v_mfma_f32_16x16x32_bf16 v[52:55], v[148:151], v[202:205], v[52:55]
	v_mfma_f32_16x16x32_bf16 v[36:39], v[148:151], v[210:213], v[36:39]
	v_mfma_f32_16x16x32_bf16 v[36:39], v[144:147], v[206:209], v[36:39]
	v_mfma_f32_16x16x32_bf16 v[20:23], v[144:147], v[228:231], v[20:23]
	v_mfma_f32_16x16x32_bf16 v[20:23], v[148:151], v[232:235], v[20:23]
	v_mfma_f32_16x16x32_bf16 v[4:7], v[148:151], v[240:243], v[4:7]
	v_mfma_f32_16x16x32_bf16 v[4:7], v[144:147], v[236:239], v[4:7]
	v_mfma_f32_16x16x32_bf16 v[0:3], v[180:183], v[236:239], v[0:3]
	v_mfma_f32_16x16x32_bf16 v[0:3], v[184:187], v[240:243], v[0:3]
	v_mfma_f32_16x16x32_bf16 v[12:15], v[184:187], v[232:235], v[12:15]
	v_mfma_f32_16x16x32_bf16 v[12:15], v[180:183], v[228:231], v[12:15]
	v_mfma_f32_16x16x32_bf16 v[28:31], v[180:183], v[206:209], v[28:31]
	v_mfma_f32_16x16x32_bf16 v[28:31], v[184:187], v[210:213], v[28:31]
	v_mfma_f32_16x16x32_bf16 v[44:47], v[184:187], v[202:205], v[44:47]
	v_mfma_f32_16x16x32_bf16 v[44:47], v[180:183], v[188:191], v[44:47]
	s_setprio 0
	s_barrier
	s_add_i32 s34, 0, 0x18000
	s_add_i32 s35, 0, 0x1c000
	v_add_u32_e32 v140, s34, v195
	v_add_u32_e32 v184, s35, v195
	ds_read_b128 v[128:131], v140
	ds_read_b128 v[132:135], v140 offset:1024
	ds_read_b128 v[136:139], v140 offset:2048
	ds_read_b128 v[140:143], v140 offset:3072
	ds_read_b128 v[144:147], v184
	ds_read_b128 v[148:151], v184 offset:1024
	ds_read_b128 v[180:183], v184 offset:2048
	ds_read_b128 v[184:187], v184 offset:3072
	s_add_u32 s30, s30, 0x40000
	s_addc_u32 s31, s31, 0
	s_mov_b32 m0, s51
	ds_read_b128 v[188:191], v200 offset:32768
	ds_read_b128 v[202:205], v200 offset:33792
	ds_read_b128 v[206:209], v200 offset:34816
	ds_read_b128 v[210:213], v200 offset:35840
	ds_read_b128 v[228:231], v200 offset:36864
	ds_read_b128 v[232:235], v200 offset:37888
	ds_read_b128 v[236:239], v200 offset:38912
	ds_read_b128 v[240:243], v200 offset:39936
	global_load_lds_dwordx4 v156, s[30:31]
	s_mov_b32 m0, s52
	s_nop 0
	global_load_lds_dwordx4 v154, s[30:31]
	s_waitcnt vmcnt(8)
	s_waitcnt lgkmcnt(0)
	s_barrier
	s_setprio 1
	s_waitcnt lgkmcnt(0)
	v_mfma_f32_16x16x32_bf16 v[124:127], v[128:131], v[188:191], v[124:127]
	v_mfma_f32_16x16x32_bf16 v[124:127], v[132:135], v[202:205], v[124:127]
	v_mfma_f32_16x16x32_bf16 v[112:115], v[132:135], v[210:213], v[112:115]
	v_mfma_f32_16x16x32_bf16 v[112:115], v[128:131], v[206:209], v[112:115]
	v_mfma_f32_16x16x32_bf16 v[96:99], v[128:131], v[228:231], v[96:99]
	v_mfma_f32_16x16x32_bf16 v[96:99], v[132:135], v[232:235], v[96:99]
	v_mfma_f32_16x16x32_bf16 v[80:83], v[132:135], v[240:243], v[80:83]
	v_mfma_f32_16x16x32_bf16 v[80:83], v[128:131], v[236:239], v[80:83]
	v_mfma_f32_16x16x32_bf16 v[72:75], v[136:139], v[236:239], v[72:75]
	v_mfma_f32_16x16x32_bf16 v[72:75], v[140:143], v[240:243], v[72:75]
	v_mfma_f32_16x16x32_bf16 v[88:91], v[140:143], v[232:235], v[88:91]
	v_mfma_f32_16x16x32_bf16 v[88:91], v[136:139], v[228:231], v[88:91]
	v_mfma_f32_16x16x32_bf16 v[104:107], v[136:139], v[206:209], v[104:107]
	v_mfma_f32_16x16x32_bf16 v[104:107], v[140:143], v[210:213], v[104:107]
	v_mfma_f32_16x16x32_bf16 v[120:123], v[140:143], v[202:205], v[120:123]
	v_mfma_f32_16x16x32_bf16 v[120:123], v[136:139], v[188:191], v[120:123]
	s_setprio 0
	s_setprio 1
	v_mfma_f32_16x16x32_bf16 v[116:119], v[144:147], v[188:191], v[116:119]
	v_mfma_f32_16x16x32_bf16 v[116:119], v[148:151], v[202:205], v[116:119]
	v_mfma_f32_16x16x32_bf16 v[100:103], v[148:151], v[210:213], v[100:103]
	v_mfma_f32_16x16x32_bf16 v[100:103], v[144:147], v[206:209], v[100:103]
	v_mfma_f32_16x16x32_bf16 v[84:87], v[144:147], v[228:231], v[84:87]
	v_mfma_f32_16x16x32_bf16 v[84:87], v[148:151], v[232:235], v[84:87]
	v_mfma_f32_16x16x32_bf16 v[68:71], v[148:151], v[240:243], v[68:71]
	v_mfma_f32_16x16x32_bf16 v[68:71], v[144:147], v[236:239], v[68:71]
	v_mfma_f32_16x16x32_bf16 v[64:67], v[180:183], v[236:239], v[64:67]
	v_mfma_f32_16x16x32_bf16 v[64:67], v[184:187], v[240:243], v[64:67]
	v_mfma_f32_16x16x32_bf16 v[76:79], v[184:187], v[232:235], v[76:79]
	v_mfma_f32_16x16x32_bf16 v[76:79], v[180:183], v[228:231], v[76:79]
	v_mfma_f32_16x16x32_bf16 v[92:95], v[180:183], v[206:209], v[92:95]
	v_mfma_f32_16x16x32_bf16 v[92:95], v[184:187], v[210:213], v[92:95]
	v_mfma_f32_16x16x32_bf16 v[108:111], v[184:187], v[202:205], v[108:111]
	v_mfma_f32_16x16x32_bf16 v[108:111], v[180:183], v[188:191], v[108:111]
	s_setprio 0
	s_barrier
	s_add_i32 s30, s34, s45
	s_mov_b32 m0, s30
	ds_read_b128 v[188:191], v200 offset:49152
	ds_read_b128 v[202:205], v200 offset:50176
	ds_read_b128 v[206:209], v200 offset:51200
	ds_read_b128 v[210:213], v200 offset:52224
	ds_read_b128 v[228:231], v200 offset:53248
	ds_read_b128 v[232:235], v200 offset:54272
	ds_read_b128 v[236:239], v200 offset:55296
	ds_read_b128 v[240:243], v200 offset:56320
	global_load_lds_dwordx4 v168, s[98:99]
	s_add_i32 m0, s30, 0x2000
	s_add_u32 s26, s26, 0x40080
	s_addc_u32 s27, s27, 0
	s_add_i32 s30, s35, s45
	global_load_lds_dwordx4 v152, s[98:99]
	s_mov_b32 m0, s30
	s_nop 0
	global_load_lds_dwordx4 v168, s[26:27]
	s_add_i32 m0, s30, 0x2000
	s_nop 0
	global_load_lds_dwordx4 v152, s[26:27]
	s_mov_b32 m0, s24
	s_nop 0
	global_load_lds_dwordx4 v156, s[100:101]
	s_mov_b32 m0, s53
	s_nop 0
	global_load_lds_dwordx4 v154, s[100:101]
	s_waitcnt vmcnt(8)
	s_waitcnt lgkmcnt(0)
	s_barrier
	s_setprio 1
	s_waitcnt lgkmcnt(0)
	v_mfma_f32_16x16x32_bf16 v[60:63], v[128:131], v[188:191], v[60:63]
	v_mfma_f32_16x16x32_bf16 v[60:63], v[132:135], v[202:205], v[60:63]
	v_mfma_f32_16x16x32_bf16 v[48:51], v[132:135], v[210:213], v[48:51]
	v_mfma_f32_16x16x32_bf16 v[48:51], v[128:131], v[206:209], v[48:51]
	v_mfma_f32_16x16x32_bf16 v[32:35], v[128:131], v[228:231], v[32:35]
	v_mfma_f32_16x16x32_bf16 v[32:35], v[132:135], v[232:235], v[32:35]
	v_mfma_f32_16x16x32_bf16 v[16:19], v[132:135], v[240:243], v[16:19]
	v_mfma_f32_16x16x32_bf16 v[16:19], v[128:131], v[236:239], v[16:19]
	v_mfma_f32_16x16x32_bf16 v[8:11], v[136:139], v[236:239], v[8:11]
	v_mfma_f32_16x16x32_bf16 v[8:11], v[140:143], v[240:243], v[8:11]
	v_mfma_f32_16x16x32_bf16 v[24:27], v[140:143], v[232:235], v[24:27]
	v_mfma_f32_16x16x32_bf16 v[24:27], v[136:139], v[228:231], v[24:27]
	v_mfma_f32_16x16x32_bf16 v[40:43], v[136:139], v[206:209], v[40:43]
	v_mfma_f32_16x16x32_bf16 v[40:43], v[140:143], v[210:213], v[40:43]
	v_mfma_f32_16x16x32_bf16 v[56:59], v[140:143], v[202:205], v[56:59]
	v_mfma_f32_16x16x32_bf16 v[56:59], v[136:139], v[188:191], v[56:59]
	s_setprio 0
	s_setprio 1
	v_mfma_f32_16x16x32_bf16 v[52:55], v[144:147], v[188:191], v[52:55]
	v_mfma_f32_16x16x32_bf16 v[52:55], v[148:151], v[202:205], v[52:55]
	v_mfma_f32_16x16x32_bf16 v[36:39], v[148:151], v[210:213], v[36:39]
	v_mfma_f32_16x16x32_bf16 v[36:39], v[144:147], v[206:209], v[36:39]
	v_mfma_f32_16x16x32_bf16 v[20:23], v[144:147], v[228:231], v[20:23]
	v_mfma_f32_16x16x32_bf16 v[20:23], v[148:151], v[232:235], v[20:23]
	v_mfma_f32_16x16x32_bf16 v[4:7], v[148:151], v[240:243], v[4:7]
	v_mfma_f32_16x16x32_bf16 v[4:7], v[144:147], v[236:239], v[4:7]
	v_mfma_f32_16x16x32_bf16 v[0:3], v[180:183], v[236:239], v[0:3]
	v_mfma_f32_16x16x32_bf16 v[0:3], v[184:187], v[240:243], v[0:3]
	v_mfma_f32_16x16x32_bf16 v[12:15], v[184:187], v[232:235], v[12:15]
	v_mfma_f32_16x16x32_bf16 v[12:15], v[180:183], v[228:231], v[12:15]
	v_mfma_f32_16x16x32_bf16 v[28:31], v[180:183], v[206:209], v[28:31]
	v_mfma_f32_16x16x32_bf16 v[28:31], v[184:187], v[210:213], v[28:31]
	v_mfma_f32_16x16x32_bf16 v[44:47], v[184:187], v[202:205], v[44:47]
	v_mfma_f32_16x16x32_bf16 v[44:47], v[180:183], v[188:191], v[44:47]
	s_setprio 0
	s_barrier
	s_add_i32 s59, s59, 2
	s_add_u32 s22, s22, 0x100
	s_addc_u32 s23, s23, 0
	s_add_u32 s57, s57, 0x100
	s_addc_u32 s58, s58, 0
	s_cmp_gt_u32 s59, 13
	s_cbranch_scc0 .LBB0_178
	s_and_b64 vcc, exec, s[10:11]
	s_cbranch_vccz .LBB0_181
	s_barrier

.LBB0_776:
	s_add_u32 s26, s22, 0xfffc0080
	s_addc_u32 s27, s23, -1
	s_add_i32 s36, 0, 0x10000
	s_cmp_eq_u32 s55, 12
	s_cselect_b32 s31, s15, s27
	s_cselect_b32 s30, s51, s26
	s_cselect_b32 s27, s13, s54
	s_cselect_b32 s26, s52, s53
	s_add_i32 s56, 0, 0x14000
	v_add_u32_e32 v140, s36, v204
	v_add_u32_e32 v156, s56, v204
	ds_read_b128 v[128:131], v140
	ds_read_b128 v[132:135], v140 offset:1024
	ds_read_b128 v[136:139], v140 offset:2048
	ds_read_b128 v[140:143], v140 offset:3072
	ds_read_b128 v[144:147], v156
	ds_read_b128 v[148:151], v156 offset:1024
	ds_read_b128 v[152:155], v156 offset:2048
	ds_read_b128 v[156:159], v156 offset:3072
	s_add_i32 m0, s42, 0xc000
	ds_read_b128 v[182:185], v206
	ds_read_b128 v[186:189], v206 offset:1024
	ds_read_b128 v[190:193], v206 offset:2048
	ds_read_b128 v[194:197], v206 offset:3072
	ds_read_b128 v[198:201], v206 offset:4096
	ds_read_b128 v[208:211], v206 offset:5120
	ds_read_b128 v[212:215], v206 offset:6144
	ds_read_b128 v[228:231], v206 offset:7168
	global_load_lds_dwordx4 v166, s[22:23]
	s_add_i32 m0, s42, 0xe000
	s_nop 0
	global_load_lds_dwordx4 v180, s[22:23]
	s_waitcnt vmcnt(8)
	s_waitcnt lgkmcnt(0)
	s_barrier
	s_setprio 1
	s_waitcnt lgkmcnt(0)
	v_mfma_f32_16x16x32_bf16 v[124:127], v[128:131], v[182:185], v[124:127]
	v_mfma_f32_16x16x32_bf16 v[124:127], v[132:135], v[186:189], v[124:127]
	v_mfma_f32_16x16x32_bf16 v[108:111], v[132:135], v[194:197], v[108:111]
	v_mfma_f32_16x16x32_bf16 v[108:111], v[128:131], v[190:193], v[108:111]
	v_mfma_f32_16x16x32_bf16 v[92:95], v[128:131], v[198:201], v[92:95]
	v_mfma_f32_16x16x32_bf16 v[92:95], v[132:135], v[208:211], v[92:95]
	v_mfma_f32_16x16x32_bf16 v[76:79], v[132:135], v[228:231], v[76:79]
	v_mfma_f32_16x16x32_bf16 v[76:79], v[128:131], v[212:215], v[76:79]
	v_mfma_f32_16x16x32_bf16 v[72:75], v[136:139], v[212:215], v[72:75]
	v_mfma_f32_16x16x32_bf16 v[72:75], v[140:143], v[228:231], v[72:75]
	v_mfma_f32_16x16x32_bf16 v[88:91], v[140:143], v[208:211], v[88:91]
	v_mfma_f32_16x16x32_bf16 v[88:91], v[136:139], v[198:201], v[88:91]
	v_mfma_f32_16x16x32_bf16 v[104:107], v[136:139], v[190:193], v[104:107]
	v_mfma_f32_16x16x32_bf16 v[104:107], v[140:143], v[194:197], v[104:107]
	v_mfma_f32_16x16x32_bf16 v[120:123], v[140:143], v[186:189], v[120:123]
	v_mfma_f32_16x16x32_bf16 v[120:123], v[136:139], v[182:185], v[120:123]
	s_setprio 0
	s_setprio 1
	v_mfma_f32_16x16x32_bf16 v[116:119], v[144:147], v[182:185], v[116:119]
	v_mfma_f32_16x16x32_bf16 v[116:119], v[148:151], v[186:189], v[116:119]
	v_mfma_f32_16x16x32_bf16 v[100:103], v[148:151], v[194:197], v[100:103]
	v_mfma_f32_16x16x32_bf16 v[100:103], v[144:147], v[190:193], v[100:103]
	v_mfma_f32_16x16x32_bf16 v[84:87], v[144:147], v[198:201], v[84:87]
	v_mfma_f32_16x16x32_bf16 v[84:87], v[148:151], v[208:211], v[84:87]
	v_mfma_f32_16x16x32_bf16 v[68:71], v[148:151], v[228:231], v[68:71]
	v_mfma_f32_16x16x32_bf16 v[68:71], v[144:147], v[212:215], v[68:71]
	v_mfma_f32_16x16x32_bf16 v[64:67], v[152:155], v[212:215], v[64:67]
	v_mfma_f32_16x16x32_bf16 v[64:67], v[156:159], v[228:231], v[64:67]
	v_mfma_f32_16x16x32_bf16 v[80:83], v[156:159], v[208:211], v[80:83]
	v_mfma_f32_16x16x32_bf16 v[80:83], v[152:155], v[198:201], v[80:83]
	v_mfma_f32_16x16x32_bf16 v[96:99], v[152:155], v[190:193], v[96:99]
	v_mfma_f32_16x16x32_bf16 v[96:99], v[156:159], v[194:197], v[96:99]
	v_mfma_f32_16x16x32_bf16 v[112:115], v[156:159], v[186:189], v[112:115]
	v_mfma_f32_16x16x32_bf16 v[112:115], v[152:155], v[182:185], v[112:115]
	s_setprio 0
	s_barrier
	s_add_i32 s36, s36, s35
	s_add_u32 s98, s26, s20
	s_addc_u32 s99, s27, s21
	s_mov_b32 m0, s36
	ds_read_b128 v[182:185], v206 offset:16384
	ds_read_b128 v[186:189], v206 offset:17408
	ds_read_b128 v[190:193], v206 offset:18432
	ds_read_b128 v[194:197], v206 offset:19456
	ds_read_b128 v[198:201], v206 offset:20480
	ds_read_b128 v[208:211], v206 offset:21504
	ds_read_b128 v[212:215], v206 offset:22528
	ds_read_b128 v[228:231], v206 offset:23552
	global_load_lds_dwordx4 v168, s[26:27]
	s_add_i32 m0, s36, 0x2000
	s_add_u32 s36, s26, 0x40000
	s_addc_u32 s37, s27, 0
	s_add_i32 s56, s56, s35
	global_load_lds_dwordx4 v160, s[26:27]
	s_mov_b32 m0, s56
	s_nop 0
	global_load_lds_dwordx4 v168, s[36:37]
	s_add_i32 m0, s56, 0x2000
	s_nop 0
	global_load_lds_dwordx4 v160, s[36:37]
	s_add_u32 s100, s30, s20
	s_addc_u32 s101, s31, s21
	s_mov_b32 m0, s42
	s_nop 0
	global_load_lds_dwordx4 v164, s[30:31]
	s_mov_b32 m0, s43
	s_nop 0
	global_load_lds_dwordx4 v162, s[30:31]
	s_waitcnt vmcnt(8)
	s_waitcnt lgkmcnt(0)
	s_barrier
	s_setprio 1
	s_waitcnt lgkmcnt(0)
	v_mfma_f32_16x16x32_bf16 v[60:63], v[128:131], v[182:185], v[60:63]
	v_mfma_f32_16x16x32_bf16 v[60:63], v[132:135], v[186:189], v[60:63]
	v_mfma_f32_16x16x32_bf16 v[44:47], v[132:135], v[194:197], v[44:47]
	v_mfma_f32_16x16x32_bf16 v[44:47], v[128:131], v[190:193], v[44:47]
	v_mfma_f32_16x16x32_bf16 v[28:31], v[128:131], v[198:201], v[28:31]
	v_mfma_f32_16x16x32_bf16 v[28:31], v[132:135], v[208:211], v[28:31]
	v_mfma_f32_16x16x32_bf16 v[12:15], v[132:135], v[228:231], v[12:15]
	v_mfma_f32_16x16x32_bf16 v[12:15], v[128:131], v[212:215], v[12:15]
	v_mfma_f32_16x16x32_bf16 v[8:11], v[136:139], v[212:215], v[8:11]
	v_mfma_f32_16x16x32_bf16 v[8:11], v[140:143], v[228:231], v[8:11]
	v_mfma_f32_16x16x32_bf16 v[24:27], v[140:143], v[208:211], v[24:27]
	v_mfma_f32_16x16x32_bf16 v[24:27], v[136:139], v[198:201], v[24:27]
	v_mfma_f32_16x16x32_bf16 v[40:43], v[136:139], v[190:193], v[40:43]
	v_mfma_f32_16x16x32_bf16 v[40:43], v[140:143], v[194:197], v[40:43]
	v_mfma_f32_16x16x32_bf16 v[56:59], v[140:143], v[186:189], v[56:59]
	v_mfma_f32_16x16x32_bf16 v[56:59], v[136:139], v[182:185], v[56:59]
	s_setprio 0
	s_setprio 1
	v_mfma_f32_16x16x32_bf16 v[52:55], v[144:147], v[182:185], v[52:55]
	v_mfma_f32_16x16x32_bf16 v[52:55], v[148:151], v[186:189], v[52:55]
	v_mfma_f32_16x16x32_bf16 v[36:39], v[148:151], v[194:197], v[36:39]
	v_mfma_f32_16x16x32_bf16 v[36:39], v[144:147], v[190:193], v[36:39]
	v_mfma_f32_16x16x32_bf16 v[20:23], v[144:147], v[198:201], v[20:23]
	v_mfma_f32_16x16x32_bf16 v[20:23], v[148:151], v[208:211], v[20:23]
	v_mfma_f32_16x16x32_bf16 v[4:7], v[148:151], v[228:231], v[4:7]
	v_mfma_f32_16x16x32_bf16 v[4:7], v[144:147], v[212:215], v[4:7]
	v_mfma_f32_16x16x32_bf16 v[0:3], v[152:155], v[212:215], v[0:3]
	v_mfma_f32_16x16x32_bf16 v[0:3], v[156:159], v[228:231], v[0:3]
	v_mfma_f32_16x16x32_bf16 v[16:19], v[156:159], v[208:211], v[16:19]
	v_mfma_f32_16x16x32_bf16 v[16:19], v[152:155], v[198:201], v[16:19]
	v_mfma_f32_16x16x32_bf16 v[32:35], v[152:155], v[190:193], v[32:35]
	v_mfma_f32_16x16x32_bf16 v[32:35], v[156:159], v[194:197], v[32:35]
	v_mfma_f32_16x16x32_bf16 v[48:51], v[156:159], v[186:189], v[48:51]
	v_mfma_f32_16x16x32_bf16 v[48:51], v[152:155], v[182:185], v[48:51]
	s_setprio 0
	s_barrier
	s_add_i32 s36, 0, 0x18000
	s_add_i32 s37, 0, 0x1c000
	v_add_u32_e32 v140, s36, v204
	v_add_u32_e32 v156, s37, v204
	ds_read_b128 v[128:131], v140
	ds_read_b128 v[132:135], v140 offset:1024
	ds_read_b128 v[136:139], v140 offset:2048
	ds_read_b128 v[140:143], v140 offset:3072
	ds_read_b128 v[144:147], v156
	ds_read_b128 v[148:151], v156 offset:1024
	ds_read_b128 v[152:155], v156 offset:2048
	ds_read_b128 v[156:159], v156 offset:3072
	s_add_u32 s30, s30, 0x40000
	s_addc_u32 s31, s31, 0
	s_mov_b32 m0, s44
	ds_read_b128 v[182:185], v206 offset:32768
	ds_read_b128 v[186:189], v206 offset:33792
	ds_read_b128 v[190:193], v206 offset:34816
	ds_read_b128 v[194:197], v206 offset:35840
	ds_read_b128 v[198:201], v206 offset:36864
	ds_read_b128 v[208:211], v206 offset:37888
	ds_read_b128 v[212:215], v206 offset:38912
	ds_read_b128 v[228:231], v206 offset:39936
	global_load_lds_dwordx4 v164, s[30:31]
	s_mov_b32 m0, s45
	s_nop 0
	global_load_lds_dwordx4 v162, s[30:31]
	s_waitcnt vmcnt(8)
	s_waitcnt lgkmcnt(0)
	s_barrier
	s_setprio 1
	s_waitcnt lgkmcnt(0)
	v_mfma_f32_16x16x32_bf16 v[124:127], v[128:131], v[182:185], v[124:127]
	v_mfma_f32_16x16x32_bf16 v[124:127], v[132:135], v[186:189], v[124:127]
	v_mfma_f32_16x16x32_bf16 v[108:111], v[132:135], v[194:197], v[108:111]
	v_mfma_f32_16x16x32_bf16 v[108:111], v[128:131], v[190:193], v[108:111]
	v_mfma_f32_16x16x32_bf16 v[92:95], v[128:131], v[198:201], v[92:95]
	v_mfma_f32_16x16x32_bf16 v[92:95], v[132:135], v[208:211], v[92:95]
	v_mfma_f32_16x16x32_bf16 v[76:79], v[132:135], v[228:231], v[76:79]
	v_mfma_f32_16x16x32_bf16 v[76:79], v[128:131], v[212:215], v[76:79]
	v_mfma_f32_16x16x32_bf16 v[72:75], v[136:139], v[212:215], v[72:75]
	v_mfma_f32_16x16x32_bf16 v[72:75], v[140:143], v[228:231], v[72:75]
	v_mfma_f32_16x16x32_bf16 v[88:91], v[140:143], v[208:211], v[88:91]
	v_mfma_f32_16x16x32_bf16 v[88:91], v[136:139], v[198:201], v[88:91]
	v_mfma_f32_16x16x32_bf16 v[104:107], v[136:139], v[190:193], v[104:107]
	v_mfma_f32_16x16x32_bf16 v[104:107], v[140:143], v[194:197], v[104:107]
	v_mfma_f32_16x16x32_bf16 v[120:123], v[140:143], v[186:189], v[120:123]
	v_mfma_f32_16x16x32_bf16 v[120:123], v[136:139], v[182:185], v[120:123]
	s_setprio 0
	s_setprio 1
	v_mfma_f32_16x16x32_bf16 v[116:119], v[144:147], v[182:185], v[116:119]
	v_mfma_f32_16x16x32_bf16 v[116:119], v[148:151], v[186:189], v[116:119]
	v_mfma_f32_16x16x32_bf16 v[100:103], v[148:151], v[194:197], v[100:103]
	v_mfma_f32_16x16x32_bf16 v[100:103], v[144:147], v[190:193], v[100:103]
	v_mfma_f32_16x16x32_bf16 v[84:87], v[144:147], v[198:201], v[84:87]
	v_mfma_f32_16x16x32_bf16 v[84:87], v[148:151], v[208:211], v[84:87]
	v_mfma_f32_16x16x32_bf16 v[68:71], v[148:151], v[228:231], v[68:71]
	v_mfma_f32_16x16x32_bf16 v[68:71], v[144:147], v[212:215], v[68:71]
	v_mfma_f32_16x16x32_bf16 v[64:67], v[152:155], v[212:215], v[64:67]
	v_mfma_f32_16x16x32_bf16 v[64:67], v[156:159], v[228:231], v[64:67]
	v_mfma_f32_16x16x32_bf16 v[80:83], v[156:159], v[208:211], v[80:83]
	v_mfma_f32_16x16x32_bf16 v[80:83], v[152:155], v[198:201], v[80:83]
	v_mfma_f32_16x16x32_bf16 v[96:99], v[152:155], v[190:193], v[96:99]
	v_mfma_f32_16x16x32_bf16 v[96:99], v[156:159], v[194:197], v[96:99]
	v_mfma_f32_16x16x32_bf16 v[112:115], v[156:159], v[186:189], v[112:115]
	v_mfma_f32_16x16x32_bf16 v[112:115], v[152:155], v[182:185], v[112:115]
	s_setprio 0
	s_barrier
	s_add_i32 s30, s36, s35
	s_mov_b32 m0, s30
	ds_read_b128 v[182:185], v206 offset:49152
	ds_read_b128 v[186:189], v206 offset:50176
	ds_read_b128 v[190:193], v206 offset:51200
	ds_read_b128 v[194:197], v206 offset:52224
	ds_read_b128 v[198:201], v206 offset:53248
	ds_read_b128 v[208:211], v206 offset:54272
	ds_read_b128 v[212:215], v206 offset:55296
	ds_read_b128 v[228:231], v206 offset:56320
	global_load_lds_dwordx4 v168, s[98:99]
	s_add_i32 m0, s30, 0x2000
	s_add_u32 s26, s26, 0x40080
	s_addc_u32 s27, s27, 0
	s_add_i32 s30, s37, s35
	global_load_lds_dwordx4 v160, s[98:99]
	s_mov_b32 m0, s30
	s_nop 0
	global_load_lds_dwordx4 v168, s[26:27]
	s_add_i32 m0, s30, 0x2000
	s_nop 0
	global_load_lds_dwordx4 v160, s[26:27]
	s_mov_b32 m0, s47
	s_nop 0
	global_load_lds_dwordx4 v164, s[100:101]
	s_mov_b32 m0, s48
	s_nop 0
	global_load_lds_dwordx4 v162, s[100:101]
	s_waitcnt vmcnt(8)
	s_waitcnt lgkmcnt(0)
	s_barrier
	s_setprio 1
	s_waitcnt lgkmcnt(0)
	v_mfma_f32_16x16x32_bf16 v[60:63], v[128:131], v[182:185], v[60:63]
	v_mfma_f32_16x16x32_bf16 v[60:63], v[132:135], v[186:189], v[60:63]
	v_mfma_f32_16x16x32_bf16 v[44:47], v[132:135], v[194:197], v[44:47]
	v_mfma_f32_16x16x32_bf16 v[44:47], v[128:131], v[190:193], v[44:47]
	v_mfma_f32_16x16x32_bf16 v[28:31], v[128:131], v[198:201], v[28:31]
	v_mfma_f32_16x16x32_bf16 v[28:31], v[132:135], v[208:211], v[28:31]
	v_mfma_f32_16x16x32_bf16 v[12:15], v[132:135], v[228:231], v[12:15]
	v_mfma_f32_16x16x32_bf16 v[12:15], v[128:131], v[212:215], v[12:15]
	v_mfma_f32_16x16x32_bf16 v[8:11], v[136:139], v[212:215], v[8:11]
	v_mfma_f32_16x16x32_bf16 v[8:11], v[140:143], v[228:231], v[8:11]
	v_mfma_f32_16x16x32_bf16 v[24:27], v[140:143], v[208:211], v[24:27]
	v_mfma_f32_16x16x32_bf16 v[24:27], v[136:139], v[198:201], v[24:27]
	v_mfma_f32_16x16x32_bf16 v[40:43], v[136:139], v[190:193], v[40:43]
	v_mfma_f32_16x16x32_bf16 v[40:43], v[140:143], v[194:197], v[40:43]
	v_mfma_f32_16x16x32_bf16 v[56:59], v[140:143], v[186:189], v[56:59]
	v_mfma_f32_16x16x32_bf16 v[56:59], v[136:139], v[182:185], v[56:59]
	s_setprio 0
	s_setprio 1
	v_mfma_f32_16x16x32_bf16 v[52:55], v[144:147], v[182:185], v[52:55]
	v_mfma_f32_16x16x32_bf16 v[52:55], v[148:151], v[186:189], v[52:55]
	v_mfma_f32_16x16x32_bf16 v[36:39], v[148:151], v[194:197], v[36:39]
	v_mfma_f32_16x16x32_bf16 v[36:39], v[144:147], v[190:193], v[36:39]
	v_mfma_f32_16x16x32_bf16 v[20:23], v[144:147], v[198:201], v[20:23]
	v_mfma_f32_16x16x32_bf16 v[20:23], v[148:151], v[208:211], v[20:23]
	v_mfma_f32_16x16x32_bf16 v[4:7], v[148:151], v[228:231], v[4:7]
	v_mfma_f32_16x16x32_bf16 v[4:7], v[144:147], v[212:215], v[4:7]
	v_mfma_f32_16x16x32_bf16 v[0:3], v[152:155], v[212:215], v[0:3]
	v_mfma_f32_16x16x32_bf16 v[0:3], v[156:159], v[228:231], v[0:3]
	v_mfma_f32_16x16x32_bf16 v[16:19], v[156:159], v[208:211], v[16:19]
	v_mfma_f32_16x16x32_bf16 v[16:19], v[152:155], v[198:201], v[16:19]
	v_mfma_f32_16x16x32_bf16 v[32:35], v[152:155], v[190:193], v[32:35]
	v_mfma_f32_16x16x32_bf16 v[32:35], v[156:159], v[194:197], v[32:35]
	v_mfma_f32_16x16x32_bf16 v[48:51], v[156:159], v[186:189], v[48:51]
	v_mfma_f32_16x16x32_bf16 v[48:51], v[152:155], v[182:185], v[48:51]
	s_setprio 0
	s_barrier
	s_add_i32 s55, s55, 2
	s_add_u32 s22, s22, 0x100
	s_addc_u32 s23, s23, 0
	s_add_u32 s53, s53, 0x100
	s_addc_u32 s54, s54, 0
	s_cmp_gt_u32 s55, 13
	s_cbranch_scc0 .LBB0_776
	s_and_b64 vcc, exec, s[10:11]
	s_cbranch_vccz .LBB0_779
	s_barrier

.LBB0_890:
	s_add_u32 s18, s0, 0xfffc0080
	s_addc_u32 s19, s1, -1
	s_add_i32 s36, 0, 0x10000
	s_cmp_eq_u32 s50, 12
	s_cselect_b32 s23, s13, s19
	s_cselect_b32 s22, s46, s18
	s_cselect_b32 s19, s11, s49
	s_cselect_b32 s18, s47, s48
	s_add_i32 s51, 0, 0x14000
	v_add_u32_e32 v140, s36, v193
	v_add_u32_e32 v180, s51, v193
	ds_read_b128 v[128:131], v140
	ds_read_b128 v[132:135], v140 offset:1024
	ds_read_b128 v[136:139], v140 offset:2048
	ds_read_b128 v[140:143], v140 offset:3072
	ds_read_b128 v[144:147], v180
	ds_read_b128 v[148:151], v180 offset:1024
	ds_read_b128 v[164:167], v180 offset:2048
	ds_read_b128 v[180:183], v180 offset:3072
	s_add_i32 m0, s30, 0xc000
	ds_read_b128 v[184:187], v198
	ds_read_b128 v[188:191], v198 offset:1024
	ds_read_b128 v[200:203], v198 offset:2048
	ds_read_b128 v[204:207], v198 offset:3072
	ds_read_b128 v[208:211], v198 offset:4096
	ds_read_b128 v[212:215], v198 offset:5120
	ds_read_b128 v[228:231], v198 offset:6144
	ds_read_b128 v[232:235], v198 offset:7168
	global_load_lds_dwordx4 v160, s[0:1]
	s_add_i32 m0, s30, 0xe000
	s_nop 0
	global_load_lds_dwordx4 v162, s[0:1]
	s_waitcnt vmcnt(8)
	s_waitcnt lgkmcnt(0)
	s_barrier
	s_setprio 1
	s_waitcnt lgkmcnt(0)
	v_mfma_f32_16x16x32_bf16 v[124:127], v[128:131], v[184:187], v[124:127]
	v_mfma_f32_16x16x32_bf16 v[124:127], v[132:135], v[188:191], v[124:127]
	v_mfma_f32_16x16x32_bf16 v[108:111], v[132:135], v[204:207], v[108:111]
	v_mfma_f32_16x16x32_bf16 v[108:111], v[128:131], v[200:203], v[108:111]
	v_mfma_f32_16x16x32_bf16 v[92:95], v[128:131], v[208:211], v[92:95]
	v_mfma_f32_16x16x32_bf16 v[92:95], v[132:135], v[212:215], v[92:95]
	v_mfma_f32_16x16x32_bf16 v[76:79], v[132:135], v[232:235], v[76:79]
	v_mfma_f32_16x16x32_bf16 v[76:79], v[128:131], v[228:231], v[76:79]
	v_mfma_f32_16x16x32_bf16 v[72:75], v[136:139], v[228:231], v[72:75]
	v_mfma_f32_16x16x32_bf16 v[72:75], v[140:143], v[232:235], v[72:75]
	v_mfma_f32_16x16x32_bf16 v[88:91], v[140:143], v[212:215], v[88:91]
	v_mfma_f32_16x16x32_bf16 v[88:91], v[136:139], v[208:211], v[88:91]
	v_mfma_f32_16x16x32_bf16 v[104:107], v[136:139], v[200:203], v[104:107]
	v_mfma_f32_16x16x32_bf16 v[104:107], v[140:143], v[204:207], v[104:107]
	v_mfma_f32_16x16x32_bf16 v[120:123], v[140:143], v[188:191], v[120:123]
	v_mfma_f32_16x16x32_bf16 v[120:123], v[136:139], v[184:187], v[120:123]
	s_setprio 0
	s_setprio 1
	v_mfma_f32_16x16x32_bf16 v[116:119], v[144:147], v[184:187], v[116:119]
	v_mfma_f32_16x16x32_bf16 v[116:119], v[148:151], v[188:191], v[116:119]
	v_mfma_f32_16x16x32_bf16 v[100:103], v[148:151], v[204:207], v[100:103]
	v_mfma_f32_16x16x32_bf16 v[100:103], v[144:147], v[200:203], v[100:103]
	v_mfma_f32_16x16x32_bf16 v[84:87], v[144:147], v[208:211], v[84:87]
	v_mfma_f32_16x16x32_bf16 v[84:87], v[148:151], v[212:215], v[84:87]
	v_mfma_f32_16x16x32_bf16 v[68:71], v[148:151], v[232:235], v[68:71]
	v_mfma_f32_16x16x32_bf16 v[68:71], v[144:147], v[228:231], v[68:71]
	v_mfma_f32_16x16x32_bf16 v[64:67], v[164:167], v[228:231], v[64:67]
	v_mfma_f32_16x16x32_bf16 v[64:67], v[180:183], v[232:235], v[64:67]
	v_mfma_f32_16x16x32_bf16 v[80:83], v[180:183], v[212:215], v[80:83]
	v_mfma_f32_16x16x32_bf16 v[80:83], v[164:167], v[208:211], v[80:83]
	v_mfma_f32_16x16x32_bf16 v[96:99], v[164:167], v[200:203], v[96:99]
	v_mfma_f32_16x16x32_bf16 v[96:99], v[180:183], v[204:207], v[96:99]
	v_mfma_f32_16x16x32_bf16 v[112:115], v[180:183], v[188:191], v[112:115]
	v_mfma_f32_16x16x32_bf16 v[112:115], v[164:167], v[184:187], v[112:115]
	s_setprio 0
	s_barrier
	s_add_i32 s36, s36, s27
	s_add_u32 s98, s18, s20
	s_addc_u32 s99, s19, s21
	s_mov_b32 m0, s36
	ds_read_b128 v[184:187], v198 offset:16384
	ds_read_b128 v[188:191], v198 offset:17408
	ds_read_b128 v[200:203], v198 offset:18432
	ds_read_b128 v[204:207], v198 offset:19456
	ds_read_b128 v[208:211], v198 offset:20480
	ds_read_b128 v[212:215], v198 offset:21504
	ds_read_b128 v[228:231], v198 offset:22528
	ds_read_b128 v[232:235], v198 offset:23552
	global_load_lds_dwordx4 v168, s[18:19]
	s_add_i32 m0, s36, 0x2000
	s_add_u32 s36, s18, 0x40000
	s_addc_u32 s37, s19, 0
	s_add_i32 s51, s51, s27
	global_load_lds_dwordx4 v152, s[18:19]
	s_mov_b32 m0, s51
	s_nop 0
	global_load_lds_dwordx4 v168, s[36:37]
	s_add_i32 m0, s51, 0x2000
	s_nop 0
	global_load_lds_dwordx4 v152, s[36:37]
	s_add_u32 s100, s22, s20
	s_addc_u32 s101, s23, s21
	s_mov_b32 m0, s30
	s_nop 0
	global_load_lds_dwordx4 v156, s[22:23]
	s_mov_b32 m0, s31
	s_nop 0
	global_load_lds_dwordx4 v154, s[22:23]
	s_waitcnt vmcnt(8)
	s_waitcnt lgkmcnt(0)
	s_barrier
	s_setprio 1
	s_waitcnt lgkmcnt(0)
	v_mfma_f32_16x16x32_bf16 v[60:63], v[128:131], v[184:187], v[60:63]
	v_mfma_f32_16x16x32_bf16 v[60:63], v[132:135], v[188:191], v[60:63]
	v_mfma_f32_16x16x32_bf16 v[44:47], v[132:135], v[204:207], v[44:47]
	v_mfma_f32_16x16x32_bf16 v[44:47], v[128:131], v[200:203], v[44:47]
	v_mfma_f32_16x16x32_bf16 v[28:31], v[128:131], v[208:211], v[28:31]
	v_mfma_f32_16x16x32_bf16 v[28:31], v[132:135], v[212:215], v[28:31]
	v_mfma_f32_16x16x32_bf16 v[12:15], v[132:135], v[232:235], v[12:15]
	v_mfma_f32_16x16x32_bf16 v[12:15], v[128:131], v[228:231], v[12:15]
	v_mfma_f32_16x16x32_bf16 v[8:11], v[136:139], v[228:231], v[8:11]
	v_mfma_f32_16x16x32_bf16 v[8:11], v[140:143], v[232:235], v[8:11]
	v_mfma_f32_16x16x32_bf16 v[24:27], v[140:143], v[212:215], v[24:27]
	v_mfma_f32_16x16x32_bf16 v[24:27], v[136:139], v[208:211], v[24:27]
	v_mfma_f32_16x16x32_bf16 v[40:43], v[136:139], v[200:203], v[40:43]
	v_mfma_f32_16x16x32_bf16 v[40:43], v[140:143], v[204:207], v[40:43]
	v_mfma_f32_16x16x32_bf16 v[56:59], v[140:143], v[188:191], v[56:59]
	v_mfma_f32_16x16x32_bf16 v[56:59], v[136:139], v[184:187], v[56:59]
	s_setprio 0
	s_setprio 1
	v_mfma_f32_16x16x32_bf16 v[52:55], v[144:147], v[184:187], v[52:55]
	v_mfma_f32_16x16x32_bf16 v[52:55], v[148:151], v[188:191], v[52:55]
	v_mfma_f32_16x16x32_bf16 v[36:39], v[148:151], v[204:207], v[36:39]
	v_mfma_f32_16x16x32_bf16 v[36:39], v[144:147], v[200:203], v[36:39]
	v_mfma_f32_16x16x32_bf16 v[20:23], v[144:147], v[208:211], v[20:23]
	v_mfma_f32_16x16x32_bf16 v[20:23], v[148:151], v[212:215], v[20:23]
	v_mfma_f32_16x16x32_bf16 v[4:7], v[148:151], v[232:235], v[4:7]
	v_mfma_f32_16x16x32_bf16 v[4:7], v[144:147], v[228:231], v[4:7]
	v_mfma_f32_16x16x32_bf16 v[0:3], v[164:167], v[228:231], v[0:3]
	v_mfma_f32_16x16x32_bf16 v[0:3], v[180:183], v[232:235], v[0:3]
	v_mfma_f32_16x16x32_bf16 v[16:19], v[180:183], v[212:215], v[16:19]
	v_mfma_f32_16x16x32_bf16 v[16:19], v[164:167], v[208:211], v[16:19]
	v_mfma_f32_16x16x32_bf16 v[32:35], v[164:167], v[200:203], v[32:35]
	v_mfma_f32_16x16x32_bf16 v[32:35], v[180:183], v[204:207], v[32:35]
	v_mfma_f32_16x16x32_bf16 v[48:51], v[180:183], v[188:191], v[48:51]
	v_mfma_f32_16x16x32_bf16 v[48:51], v[164:167], v[184:187], v[48:51]
	s_setprio 0
	s_barrier
	s_add_i32 s36, 0, 0x18000
	s_add_i32 s37, 0, 0x1c000
	v_add_u32_e32 v140, s36, v193
	v_add_u32_e32 v180, s37, v193
	ds_read_b128 v[128:131], v140
	ds_read_b128 v[132:135], v140 offset:1024
	ds_read_b128 v[136:139], v140 offset:2048
	ds_read_b128 v[140:143], v140 offset:3072
	ds_read_b128 v[144:147], v180
	ds_read_b128 v[148:151], v180 offset:1024
	ds_read_b128 v[164:167], v180 offset:2048
	ds_read_b128 v[180:183], v180 offset:3072
	s_add_u32 s22, s22, 0x40000
	s_addc_u32 s23, s23, 0
	s_mov_b32 m0, s34
	ds_read_b128 v[184:187], v198 offset:32768
	ds_read_b128 v[188:191], v198 offset:33792
	ds_read_b128 v[200:203], v198 offset:34816
	ds_read_b128 v[204:207], v198 offset:35840
	ds_read_b128 v[208:211], v198 offset:36864
	ds_read_b128 v[212:215], v198 offset:37888
	ds_read_b128 v[228:231], v198 offset:38912
	ds_read_b128 v[232:235], v198 offset:39936
	global_load_lds_dwordx4 v156, s[22:23]
	s_mov_b32 m0, s35
	s_nop 0
	global_load_lds_dwordx4 v154, s[22:23]
	s_waitcnt vmcnt(8)
	s_waitcnt lgkmcnt(0)
	s_barrier
	s_setprio 1
	s_waitcnt lgkmcnt(0)
	v_mfma_f32_16x16x32_bf16 v[124:127], v[128:131], v[184:187], v[124:127]
	v_mfma_f32_16x16x32_bf16 v[124:127], v[132:135], v[188:191], v[124:127]
	v_mfma_f32_16x16x32_bf16 v[108:111], v[132:135], v[204:207], v[108:111]
	v_mfma_f32_16x16x32_bf16 v[108:111], v[128:131], v[200:203], v[108:111]
	v_mfma_f32_16x16x32_bf16 v[92:95], v[128:131], v[208:211], v[92:95]
	v_mfma_f32_16x16x32_bf16 v[92:95], v[132:135], v[212:215], v[92:95]
	v_mfma_f32_16x16x32_bf16 v[76:79], v[132:135], v[232:235], v[76:79]
	v_mfma_f32_16x16x32_bf16 v[76:79], v[128:131], v[228:231], v[76:79]
	v_mfma_f32_16x16x32_bf16 v[72:75], v[136:139], v[228:231], v[72:75]
	v_mfma_f32_16x16x32_bf16 v[72:75], v[140:143], v[232:235], v[72:75]
	v_mfma_f32_16x16x32_bf16 v[88:91], v[140:143], v[212:215], v[88:91]
	v_mfma_f32_16x16x32_bf16 v[88:91], v[136:139], v[208:211], v[88:91]
	v_mfma_f32_16x16x32_bf16 v[104:107], v[136:139], v[200:203], v[104:107]
	v_mfma_f32_16x16x32_bf16 v[104:107], v[140:143], v[204:207], v[104:107]
	v_mfma_f32_16x16x32_bf16 v[120:123], v[140:143], v[188:191], v[120:123]
	v_mfma_f32_16x16x32_bf16 v[120:123], v[136:139], v[184:187], v[120:123]
	s_setprio 0
	s_setprio 1
	v_mfma_f32_16x16x32_bf16 v[116:119], v[144:147], v[184:187], v[116:119]
	v_mfma_f32_16x16x32_bf16 v[116:119], v[148:151], v[188:191], v[116:119]
	v_mfma_f32_16x16x32_bf16 v[100:103], v[148:151], v[204:207], v[100:103]
	v_mfma_f32_16x16x32_bf16 v[100:103], v[144:147], v[200:203], v[100:103]
	v_mfma_f32_16x16x32_bf16 v[84:87], v[144:147], v[208:211], v[84:87]
	v_mfma_f32_16x16x32_bf16 v[84:87], v[148:151], v[212:215], v[84:87]
	v_mfma_f32_16x16x32_bf16 v[68:71], v[148:151], v[232:235], v[68:71]
	v_mfma_f32_16x16x32_bf16 v[68:71], v[144:147], v[228:231], v[68:71]
	v_mfma_f32_16x16x32_bf16 v[64:67], v[164:167], v[228:231], v[64:67]
	v_mfma_f32_16x16x32_bf16 v[64:67], v[180:183], v[232:235], v[64:67]
	v_mfma_f32_16x16x32_bf16 v[80:83], v[180:183], v[212:215], v[80:83]
	v_mfma_f32_16x16x32_bf16 v[80:83], v[164:167], v[208:211], v[80:83]
	v_mfma_f32_16x16x32_bf16 v[96:99], v[164:167], v[200:203], v[96:99]
	v_mfma_f32_16x16x32_bf16 v[96:99], v[180:183], v[204:207], v[96:99]
	v_mfma_f32_16x16x32_bf16 v[112:115], v[180:183], v[188:191], v[112:115]
	v_mfma_f32_16x16x32_bf16 v[112:115], v[164:167], v[184:187], v[112:115]
	s_setprio 0
	s_barrier
	s_add_i32 s22, s36, s27
	s_mov_b32 m0, s22
	ds_read_b128 v[184:187], v198 offset:49152
	ds_read_b128 v[188:191], v198 offset:50176
	ds_read_b128 v[200:203], v198 offset:51200
	ds_read_b128 v[204:207], v198 offset:52224
	ds_read_b128 v[208:211], v198 offset:53248
	ds_read_b128 v[212:215], v198 offset:54272
	ds_read_b128 v[228:231], v198 offset:55296
	ds_read_b128 v[232:235], v198 offset:56320
	global_load_lds_dwordx4 v168, s[98:99]
	s_add_i32 m0, s22, 0x2000
	s_add_u32 s18, s18, 0x40080
	s_addc_u32 s19, s19, 0
	s_add_i32 s22, s37, s27
	global_load_lds_dwordx4 v152, s[98:99]
	s_mov_b32 m0, s22
	s_nop 0
	global_load_lds_dwordx4 v168, s[18:19]
	s_add_i32 m0, s22, 0x2000
	s_nop 0
	global_load_lds_dwordx4 v152, s[18:19]
	s_mov_b32 m0, s24
	s_nop 0
	global_load_lds_dwordx4 v156, s[100:101]
	s_mov_b32 m0, s42
	s_nop 0
	global_load_lds_dwordx4 v154, s[100:101]
	s_waitcnt vmcnt(8)
	s_waitcnt lgkmcnt(0)
	s_barrier
	s_setprio 1
	s_waitcnt lgkmcnt(0)
	v_mfma_f32_16x16x32_bf16 v[60:63], v[128:131], v[184:187], v[60:63]
	v_mfma_f32_16x16x32_bf16 v[60:63], v[132:135], v[188:191], v[60:63]
	v_mfma_f32_16x16x32_bf16 v[44:47], v[132:135], v[204:207], v[44:47]
	v_mfma_f32_16x16x32_bf16 v[44:47], v[128:131], v[200:203], v[44:47]
	v_mfma_f32_16x16x32_bf16 v[28:31], v[128:131], v[208:211], v[28:31]
	v_mfma_f32_16x16x32_bf16 v[28:31], v[132:135], v[212:215], v[28:31]
	v_mfma_f32_16x16x32_bf16 v[12:15], v[132:135], v[232:235], v[12:15]
	v_mfma_f32_16x16x32_bf16 v[12:15], v[128:131], v[228:231], v[12:15]
	v_mfma_f32_16x16x32_bf16 v[8:11], v[136:139], v[228:231], v[8:11]
	v_mfma_f32_16x16x32_bf16 v[8:11], v[140:143], v[232:235], v[8:11]
	v_mfma_f32_16x16x32_bf16 v[24:27], v[140:143], v[212:215], v[24:27]
	v_mfma_f32_16x16x32_bf16 v[24:27], v[136:139], v[208:211], v[24:27]
	v_mfma_f32_16x16x32_bf16 v[40:43], v[136:139], v[200:203], v[40:43]
	v_mfma_f32_16x16x32_bf16 v[40:43], v[140:143], v[204:207], v[40:43]
	v_mfma_f32_16x16x32_bf16 v[56:59], v[140:143], v[188:191], v[56:59]
	v_mfma_f32_16x16x32_bf16 v[56:59], v[136:139], v[184:187], v[56:59]
	s_setprio 0
	s_setprio 1
	v_mfma_f32_16x16x32_bf16 v[52:55], v[144:147], v[184:187], v[52:55]
	v_mfma_f32_16x16x32_bf16 v[52:55], v[148:151], v[188:191], v[52:55]
	v_mfma_f32_16x16x32_bf16 v[36:39], v[148:151], v[204:207], v[36:39]
	v_mfma_f32_16x16x32_bf16 v[36:39], v[144:147], v[200:203], v[36:39]
	v_mfma_f32_16x16x32_bf16 v[20:23], v[144:147], v[208:211], v[20:23]
	v_mfma_f32_16x16x32_bf16 v[20:23], v[148:151], v[212:215], v[20:23]
	v_mfma_f32_16x16x32_bf16 v[4:7], v[148:151], v[232:235], v[4:7]
	v_mfma_f32_16x16x32_bf16 v[4:7], v[144:147], v[228:231], v[4:7]
	v_mfma_f32_16x16x32_bf16 v[0:3], v[164:167], v[228:231], v[0:3]
	v_mfma_f32_16x16x32_bf16 v[0:3], v[180:183], v[232:235], v[0:3]
	v_mfma_f32_16x16x32_bf16 v[16:19], v[180:183], v[212:215], v[16:19]
	v_mfma_f32_16x16x32_bf16 v[16:19], v[164:167], v[208:211], v[16:19]
	v_mfma_f32_16x16x32_bf16 v[32:35], v[164:167], v[200:203], v[32:35]
	v_mfma_f32_16x16x32_bf16 v[32:35], v[180:183], v[204:207], v[32:35]
	v_mfma_f32_16x16x32_bf16 v[48:51], v[180:183], v[188:191], v[48:51]
	v_mfma_f32_16x16x32_bf16 v[48:51], v[164:167], v[184:187], v[48:51]
	s_setprio 0
	s_barrier
	s_add_i32 s50, s50, 2
	s_add_u32 s0, s0, 0x100
	s_addc_u32 s1, s1, 0
	s_add_u32 s48, s48, 0x100
	s_addc_u32 s49, s49, 0
	s_cmp_gt_u32 s50, 13
	s_cbranch_scc0 .LBB0_890
	s_and_b64 vcc, exec, s[8:9]
	s_cbranch_vccz .LBB0_893
	s_barrier

.LBB0_986:
	s_add_u32 s34, s8, 0xfff00080
	s_addc_u32 s35, s9, -1
	s_add_i32 s36, 0, 0x10000
	s_cmp_eq_u32 s57, 60
	s_cselect_b32 s41, s23, s35
	s_cselect_b32 s40, s53, s34
	s_cselect_b32 s35, s19, s56
	s_cselect_b32 s34, s54, s55
	s_add_i32 s58, 0, 0x14000
	v_add_u32_e32 v140, s36, v228
	v_add_u32_e32 v156, s58, v228
	ds_read_b128 v[128:131], v140
	ds_read_b128 v[132:135], v140 offset:1024
	ds_read_b128 v[136:139], v140 offset:2048
	ds_read_b128 v[140:143], v140 offset:3072
	ds_read_b128 v[144:147], v156
	ds_read_b128 v[148:151], v156 offset:1024
	ds_read_b128 v[152:155], v156 offset:2048
	ds_read_b128 v[156:159], v156 offset:3072
	s_add_i32 m0, s44, 0xc000
	ds_read_b128 v[160:163], v230
	ds_read_b128 v[164:167], v230 offset:1024
	ds_read_b128 v[190:193], v230 offset:2048
	ds_read_b128 v[194:197], v230 offset:3072
	ds_read_b128 v[198:201], v230 offset:4096
	ds_read_b128 v[202:205], v230 offset:5120
	ds_read_b128 v[206:209], v230 offset:6144
	ds_read_b128 v[210:213], v230 offset:7168
	global_load_lds_dwordx4 v186, s[8:9]
	s_add_i32 m0, s44, 0xe000
	s_nop 0
	global_load_lds_dwordx4 v188, s[8:9]
	s_waitcnt vmcnt(8)
	s_waitcnt lgkmcnt(0)
	s_barrier
	s_setprio 1
	s_waitcnt lgkmcnt(0)
	v_mfma_f32_16x16x32_bf16 v[124:127], v[128:131], v[160:163], v[124:127]
	v_mfma_f32_16x16x32_bf16 v[124:127], v[132:135], v[164:167], v[124:127]
	v_mfma_f32_16x16x32_bf16 v[108:111], v[132:135], v[194:197], v[108:111]
	v_mfma_f32_16x16x32_bf16 v[108:111], v[128:131], v[190:193], v[108:111]
	v_mfma_f32_16x16x32_bf16 v[92:95], v[128:131], v[198:201], v[92:95]
	v_mfma_f32_16x16x32_bf16 v[92:95], v[132:135], v[202:205], v[92:95]
	v_mfma_f32_16x16x32_bf16 v[76:79], v[132:135], v[210:213], v[76:79]
	v_mfma_f32_16x16x32_bf16 v[76:79], v[128:131], v[206:209], v[76:79]
	v_mfma_f32_16x16x32_bf16 v[72:75], v[136:139], v[206:209], v[72:75]
	v_mfma_f32_16x16x32_bf16 v[72:75], v[140:143], v[210:213], v[72:75]
	v_mfma_f32_16x16x32_bf16 v[88:91], v[140:143], v[202:205], v[88:91]
	v_mfma_f32_16x16x32_bf16 v[88:91], v[136:139], v[198:201], v[88:91]
	v_mfma_f32_16x16x32_bf16 v[104:107], v[136:139], v[190:193], v[104:107]
	v_mfma_f32_16x16x32_bf16 v[104:107], v[140:143], v[194:197], v[104:107]
	v_mfma_f32_16x16x32_bf16 v[120:123], v[140:143], v[164:167], v[120:123]
	v_mfma_f32_16x16x32_bf16 v[120:123], v[136:139], v[160:163], v[120:123]
	s_setprio 0
	s_setprio 1
	v_mfma_f32_16x16x32_bf16 v[116:119], v[144:147], v[160:163], v[116:119]
	v_mfma_f32_16x16x32_bf16 v[116:119], v[148:151], v[164:167], v[116:119]
	v_mfma_f32_16x16x32_bf16 v[100:103], v[148:151], v[194:197], v[100:103]
	v_mfma_f32_16x16x32_bf16 v[100:103], v[144:147], v[190:193], v[100:103]
	v_mfma_f32_16x16x32_bf16 v[84:87], v[144:147], v[198:201], v[84:87]
	v_mfma_f32_16x16x32_bf16 v[84:87], v[148:151], v[202:205], v[84:87]
	v_mfma_f32_16x16x32_bf16 v[68:71], v[148:151], v[210:213], v[68:71]
	v_mfma_f32_16x16x32_bf16 v[68:71], v[144:147], v[206:209], v[68:71]
	v_mfma_f32_16x16x32_bf16 v[64:67], v[152:155], v[206:209], v[64:67]
	v_mfma_f32_16x16x32_bf16 v[64:67], v[156:159], v[210:213], v[64:67]
	v_mfma_f32_16x16x32_bf16 v[80:83], v[156:159], v[202:205], v[80:83]
	v_mfma_f32_16x16x32_bf16 v[80:83], v[152:155], v[198:201], v[80:83]
	v_mfma_f32_16x16x32_bf16 v[96:99], v[152:155], v[190:193], v[96:99]
	v_mfma_f32_16x16x32_bf16 v[96:99], v[156:159], v[194:197], v[96:99]
	v_mfma_f32_16x16x32_bf16 v[112:115], v[156:159], v[164:167], v[112:115]
	v_mfma_f32_16x16x32_bf16 v[112:115], v[152:155], v[160:163], v[112:115]
	s_setprio 0
	s_barrier
	s_add_i32 s36, s36, s43
	s_add_u32 s98, s34, s20
	s_addc_u32 s99, s35, s21
	s_mov_b32 m0, s36
	ds_read_b128 v[160:163], v230 offset:16384
	ds_read_b128 v[164:167], v230 offset:17408
	ds_read_b128 v[190:193], v230 offset:18432
	ds_read_b128 v[194:197], v230 offset:19456
	ds_read_b128 v[198:201], v230 offset:20480
	ds_read_b128 v[202:205], v230 offset:21504
	ds_read_b128 v[206:209], v230 offset:22528
	ds_read_b128 v[210:213], v230 offset:23552
	global_load_lds_dwordx4 v168, s[34:35]
	s_add_i32 m0, s36, 0x2000
	s_add_u32 s36, s34, 0x100000
	s_addc_u32 s37, s35, 0
	s_add_i32 s58, s58, s43
	global_load_lds_dwordx4 v180, s[34:35]
	s_mov_b32 m0, s58
	s_nop 0
	global_load_lds_dwordx4 v168, s[36:37]
	s_add_i32 m0, s58, 0x2000
	s_nop 0
	global_load_lds_dwordx4 v180, s[36:37]
	s_add_u32 s100, s40, s20
	s_addc_u32 s101, s41, s21
	s_mov_b32 m0, s44
	s_nop 0
	global_load_lds_dwordx4 v184, s[40:41]
	s_mov_b32 m0, s45
	s_nop 0
	global_load_lds_dwordx4 v182, s[40:41]
	s_waitcnt vmcnt(8)
	s_waitcnt lgkmcnt(0)
	s_barrier
	s_setprio 1
	s_waitcnt lgkmcnt(0)
	v_mfma_f32_16x16x32_bf16 v[60:63], v[128:131], v[160:163], v[60:63]
	v_mfma_f32_16x16x32_bf16 v[60:63], v[132:135], v[164:167], v[60:63]
	v_mfma_f32_16x16x32_bf16 v[44:47], v[132:135], v[194:197], v[44:47]
	v_mfma_f32_16x16x32_bf16 v[44:47], v[128:131], v[190:193], v[44:47]
	v_mfma_f32_16x16x32_bf16 v[28:31], v[128:131], v[198:201], v[28:31]
	v_mfma_f32_16x16x32_bf16 v[28:31], v[132:135], v[202:205], v[28:31]
	v_mfma_f32_16x16x32_bf16 v[12:15], v[132:135], v[210:213], v[12:15]
	v_mfma_f32_16x16x32_bf16 v[12:15], v[128:131], v[206:209], v[12:15]
	v_mfma_f32_16x16x32_bf16 v[8:11], v[136:139], v[206:209], v[8:11]
	v_mfma_f32_16x16x32_bf16 v[8:11], v[140:143], v[210:213], v[8:11]
	v_mfma_f32_16x16x32_bf16 v[24:27], v[140:143], v[202:205], v[24:27]
	v_mfma_f32_16x16x32_bf16 v[24:27], v[136:139], v[198:201], v[24:27]
	v_mfma_f32_16x16x32_bf16 v[40:43], v[136:139], v[190:193], v[40:43]
	v_mfma_f32_16x16x32_bf16 v[40:43], v[140:143], v[194:197], v[40:43]
	v_mfma_f32_16x16x32_bf16 v[56:59], v[140:143], v[164:167], v[56:59]
	v_mfma_f32_16x16x32_bf16 v[56:59], v[136:139], v[160:163], v[56:59]
	s_setprio 0
	s_setprio 1
	v_mfma_f32_16x16x32_bf16 v[52:55], v[144:147], v[160:163], v[52:55]
	v_mfma_f32_16x16x32_bf16 v[52:55], v[148:151], v[164:167], v[52:55]
	v_mfma_f32_16x16x32_bf16 v[36:39], v[148:151], v[194:197], v[36:39]
	v_mfma_f32_16x16x32_bf16 v[36:39], v[144:147], v[190:193], v[36:39]
	v_mfma_f32_16x16x32_bf16 v[20:23], v[144:147], v[198:201], v[20:23]
	v_mfma_f32_16x16x32_bf16 v[20:23], v[148:151], v[202:205], v[20:23]
	v_mfma_f32_16x16x32_bf16 v[4:7], v[148:151], v[210:213], v[4:7]
	v_mfma_f32_16x16x32_bf16 v[4:7], v[144:147], v[206:209], v[4:7]
	v_mfma_f32_16x16x32_bf16 v[0:3], v[152:155], v[206:209], v[0:3]
	v_mfma_f32_16x16x32_bf16 v[0:3], v[156:159], v[210:213], v[0:3]
	v_mfma_f32_16x16x32_bf16 v[16:19], v[156:159], v[202:205], v[16:19]
	v_mfma_f32_16x16x32_bf16 v[16:19], v[152:155], v[198:201], v[16:19]
	v_mfma_f32_16x16x32_bf16 v[32:35], v[152:155], v[190:193], v[32:35]
	v_mfma_f32_16x16x32_bf16 v[32:35], v[156:159], v[194:197], v[32:35]
	v_mfma_f32_16x16x32_bf16 v[48:51], v[156:159], v[164:167], v[48:51]
	v_mfma_f32_16x16x32_bf16 v[48:51], v[152:155], v[160:163], v[48:51]
	s_setprio 0
	s_barrier
	s_add_i32 s58, 0, 0x18000
	s_add_i32 s59, 0, 0x1c000
	v_add_u32_e32 v140, s58, v228
	v_add_u32_e32 v156, s59, v228
	ds_read_b128 v[128:131], v140
	ds_read_b128 v[132:135], v140 offset:1024
	ds_read_b128 v[136:139], v140 offset:2048
	ds_read_b128 v[140:143], v140 offset:3072
	ds_read_b128 v[144:147], v156
	ds_read_b128 v[148:151], v156 offset:1024
	ds_read_b128 v[152:155], v156 offset:2048
	ds_read_b128 v[156:159], v156 offset:3072
	s_add_u32 s36, s40, 0x100000
	s_addc_u32 s37, s41, 0
	s_mov_b32 m0, s46
	ds_read_b128 v[160:163], v230 offset:32768
	ds_read_b128 v[164:167], v230 offset:33792
	ds_read_b128 v[190:193], v230 offset:34816
	ds_read_b128 v[194:197], v230 offset:35840
	ds_read_b128 v[198:201], v230 offset:36864
	ds_read_b128 v[202:205], v230 offset:37888
	ds_read_b128 v[206:209], v230 offset:38912
	ds_read_b128 v[210:213], v230 offset:39936
	global_load_lds_dwordx4 v184, s[36:37]
	s_mov_b32 m0, s47
	s_nop 0
	global_load_lds_dwordx4 v182, s[36:37]
	s_waitcnt vmcnt(8)
	s_waitcnt lgkmcnt(0)
	s_barrier
	s_setprio 1
	s_waitcnt lgkmcnt(0)
	v_mfma_f32_16x16x32_bf16 v[124:127], v[128:131], v[160:163], v[124:127]
	v_mfma_f32_16x16x32_bf16 v[124:127], v[132:135], v[164:167], v[124:127]
	v_mfma_f32_16x16x32_bf16 v[108:111], v[132:135], v[194:197], v[108:111]
	v_mfma_f32_16x16x32_bf16 v[108:111], v[128:131], v[190:193], v[108:111]
	v_mfma_f32_16x16x32_bf16 v[92:95], v[128:131], v[198:201], v[92:95]
	v_mfma_f32_16x16x32_bf16 v[92:95], v[132:135], v[202:205], v[92:95]
	v_mfma_f32_16x16x32_bf16 v[76:79], v[132:135], v[210:213], v[76:79]
	v_mfma_f32_16x16x32_bf16 v[76:79], v[128:131], v[206:209], v[76:79]
	v_mfma_f32_16x16x32_bf16 v[72:75], v[136:139], v[206:209], v[72:75]
	v_mfma_f32_16x16x32_bf16 v[72:75], v[140:143], v[210:213], v[72:75]
	v_mfma_f32_16x16x32_bf16 v[88:91], v[140:143], v[202:205], v[88:91]
	v_mfma_f32_16x16x32_bf16 v[88:91], v[136:139], v[198:201], v[88:91]
	v_mfma_f32_16x16x32_bf16 v[104:107], v[136:139], v[190:193], v[104:107]
	v_mfma_f32_16x16x32_bf16 v[104:107], v[140:143], v[194:197], v[104:107]
	v_mfma_f32_16x16x32_bf16 v[120:123], v[140:143], v[164:167], v[120:123]
	v_mfma_f32_16x16x32_bf16 v[120:123], v[136:139], v[160:163], v[120:123]
	s_setprio 0
	s_setprio 1
	v_mfma_f32_16x16x32_bf16 v[116:119], v[144:147], v[160:163], v[116:119]
	v_mfma_f32_16x16x32_bf16 v[116:119], v[148:151], v[164:167], v[116:119]
	v_mfma_f32_16x16x32_bf16 v[100:103], v[148:151], v[194:197], v[100:103]
	v_mfma_f32_16x16x32_bf16 v[100:103], v[144:147], v[190:193], v[100:103]
	v_mfma_f32_16x16x32_bf16 v[84:87], v[144:147], v[198:201], v[84:87]
	v_mfma_f32_16x16x32_bf16 v[84:87], v[148:151], v[202:205], v[84:87]
	v_mfma_f32_16x16x32_bf16 v[68:71], v[148:151], v[210:213], v[68:71]
	v_mfma_f32_16x16x32_bf16 v[68:71], v[144:147], v[206:209], v[68:71]
	v_mfma_f32_16x16x32_bf16 v[64:67], v[152:155], v[206:209], v[64:67]
	v_mfma_f32_16x16x32_bf16 v[64:67], v[156:159], v[210:213], v[64:67]
	v_mfma_f32_16x16x32_bf16 v[80:83], v[156:159], v[202:205], v[80:83]
	v_mfma_f32_16x16x32_bf16 v[80:83], v[152:155], v[198:201], v[80:83]
	v_mfma_f32_16x16x32_bf16 v[96:99], v[152:155], v[190:193], v[96:99]
	v_mfma_f32_16x16x32_bf16 v[96:99], v[156:159], v[194:197], v[96:99]
	v_mfma_f32_16x16x32_bf16 v[112:115], v[156:159], v[164:167], v[112:115]
	v_mfma_f32_16x16x32_bf16 v[112:115], v[152:155], v[160:163], v[112:115]
	s_setprio 0
	s_barrier
	s_add_i32 s36, s58, s43
	s_mov_b32 m0, s36
	ds_read_b128 v[160:163], v230 offset:49152
	ds_read_b128 v[164:167], v230 offset:50176
	ds_read_b128 v[190:193], v230 offset:51200
	ds_read_b128 v[194:197], v230 offset:52224
	ds_read_b128 v[198:201], v230 offset:53248
	ds_read_b128 v[202:205], v230 offset:54272
	ds_read_b128 v[206:209], v230 offset:55296
	ds_read_b128 v[210:213], v230 offset:56320
	global_load_lds_dwordx4 v168, s[98:99]
	s_add_i32 m0, s36, 0x2000
	s_add_u32 s34, s34, 0x100080
	s_addc_u32 s35, s35, 0
	s_add_i32 s36, s59, s43
	global_load_lds_dwordx4 v180, s[98:99]
	s_mov_b32 m0, s36
	s_nop 0
	global_load_lds_dwordx4 v168, s[34:35]
	s_add_i32 m0, s36, 0x2000
	s_nop 0
	global_load_lds_dwordx4 v180, s[34:35]
	s_mov_b32 m0, s50
	s_nop 0
	global_load_lds_dwordx4 v184, s[100:101]
	s_mov_b32 m0, s51
	s_nop 0
	global_load_lds_dwordx4 v182, s[100:101]
	s_waitcnt vmcnt(8)
	s_waitcnt lgkmcnt(0)
	s_barrier
	s_setprio 1
	s_waitcnt lgkmcnt(0)
	v_mfma_f32_16x16x32_bf16 v[60:63], v[128:131], v[160:163], v[60:63]
	v_mfma_f32_16x16x32_bf16 v[60:63], v[132:135], v[164:167], v[60:63]
	v_mfma_f32_16x16x32_bf16 v[44:47], v[132:135], v[194:197], v[44:47]
	v_mfma_f32_16x16x32_bf16 v[44:47], v[128:131], v[190:193], v[44:47]
	v_mfma_f32_16x16x32_bf16 v[28:31], v[128:131], v[198:201], v[28:31]
	v_mfma_f32_16x16x32_bf16 v[28:31], v[132:135], v[202:205], v[28:31]
	v_mfma_f32_16x16x32_bf16 v[12:15], v[132:135], v[210:213], v[12:15]
	v_mfma_f32_16x16x32_bf16 v[12:15], v[128:131], v[206:209], v[12:15]
	v_mfma_f32_16x16x32_bf16 v[8:11], v[136:139], v[206:209], v[8:11]
	v_mfma_f32_16x16x32_bf16 v[8:11], v[140:143], v[210:213], v[8:11]
	v_mfma_f32_16x16x32_bf16 v[24:27], v[140:143], v[202:205], v[24:27]
	v_mfma_f32_16x16x32_bf16 v[24:27], v[136:139], v[198:201], v[24:27]
	v_mfma_f32_16x16x32_bf16 v[40:43], v[136:139], v[190:193], v[40:43]
	v_mfma_f32_16x16x32_bf16 v[40:43], v[140:143], v[194:197], v[40:43]
	v_mfma_f32_16x16x32_bf16 v[56:59], v[140:143], v[164:167], v[56:59]
	v_mfma_f32_16x16x32_bf16 v[56:59], v[136:139], v[160:163], v[56:59]
	s_setprio 0
	s_setprio 1
	v_mfma_f32_16x16x32_bf16 v[52:55], v[144:147], v[160:163], v[52:55]
	v_mfma_f32_16x16x32_bf16 v[52:55], v[148:151], v[164:167], v[52:55]
	v_mfma_f32_16x16x32_bf16 v[36:39], v[148:151], v[194:197], v[36:39]
	v_mfma_f32_16x16x32_bf16 v[36:39], v[144:147], v[190:193], v[36:39]
	v_mfma_f32_16x16x32_bf16 v[20:23], v[144:147], v[198:201], v[20:23]
	v_mfma_f32_16x16x32_bf16 v[20:23], v[148:151], v[202:205], v[20:23]
	v_mfma_f32_16x16x32_bf16 v[4:7], v[148:151], v[210:213], v[4:7]
	v_mfma_f32_16x16x32_bf16 v[4:7], v[144:147], v[206:209], v[4:7]
	v_mfma_f32_16x16x32_bf16 v[0:3], v[152:155], v[206:209], v[0:3]
	v_mfma_f32_16x16x32_bf16 v[0:3], v[156:159], v[210:213], v[0:3]
	v_mfma_f32_16x16x32_bf16 v[16:19], v[156:159], v[202:205], v[16:19]
	v_mfma_f32_16x16x32_bf16 v[16:19], v[152:155], v[198:201], v[16:19]
	v_mfma_f32_16x16x32_bf16 v[32:35], v[152:155], v[190:193], v[32:35]
	v_mfma_f32_16x16x32_bf16 v[32:35], v[156:159], v[194:197], v[32:35]
	v_mfma_f32_16x16x32_bf16 v[48:51], v[156:159], v[164:167], v[48:51]
	v_mfma_f32_16x16x32_bf16 v[48:51], v[152:155], v[160:163], v[48:51]
	s_setprio 0
	s_barrier
	s_add_i32 s57, s57, 2
	s_add_u32 s8, s8, 0x100
	s_addc_u32 s9, s9, 0
	s_add_u32 s55, s55, 0x100
	s_addc_u32 s56, s56, 0
	s_cmp_gt_u32 s57, 61
	s_cbranch_scc0 .LBB0_986
	s_and_b64 vcc, exec, s[12:13]
	s_cbranch_vccz .LBB0_989
	s_barrier
